# speedup vs baseline: 1.0003x; 1.0003x over previous
; #define MFMA32(a, b, c) __builtin_amdgcn_mfma_f32_32x32x16_bf16((a), (b), (c), 0, 0, 0)
; DI void gemm_mainloop(const bf16_t* __restrict__ A, int lda, const bf16_t* __restrict__ B, int ldb, int K,
;                       f32x16 (&acc)[2][4], char* smem, const int tid) {
;     ...
;   for (int kt = 0; kt < nk; ++kt) {
;     asm volatile("s_waitcnt vmcnt(8) lgkmcnt(0)" ::: "memory");
;     __builtin_amdgcn_s_barrier();
;     dma_stage(A, lda, B, ldb, (kt + 3) * 32, smem + ((kt + 3) & 3) * STG, w, lane);
;     const char* st = smem + (kt & 3) * STG;
;     _Pragma("unroll") for (int ks = 0; ks < 2; ++ks) {
;       const int oo = ks ? o1 : o0;
;       bf16x8 a0 = *(const bf16x8*)(st + aoff + oo);
;       bf16x8 a1 = *(const bf16x8*)(st + aoff + 32 * 64 + oo);
;       bf16x8 b0 = *(const bf16x8*)(st + boff + oo);
;       bf16x8 b1 = *(const bf16x8*)(st + boff + 32 * 64 + oo);
;       bf16x8 b2 = *(const bf16x8*)(st + boff + 64 * 64 + oo);
;       bf16x8 b3 = *(const bf16x8*)(st + boff + 96 * 64 + oo);
;       acc[0][0] = MFMA32(a0, b0, acc[0][0]); acc[0][1] = MFMA32(a0, b1, acc[0][1]);
;       acc[0][2] = MFMA32(a0, b2, acc[0][2]); acc[0][3] = MFMA32(a0, b3, acc[0][3]);
;       acc[1][0] = MFMA32(a1, b0, acc[1][0]); acc[1][1] = MFMA32(a1, b1, acc[1][1]);
;       acc[1][2] = MFMA32(a1, b2, acc[1][2]); acc[1][3] = MFMA32(a1, b3, acc[1][3]);
;     }
; DI void rstd_publish(float s, float invK, float* srstd, int tid) {
;   if (tid < 256) srstd[tid] = rsqrtf(s * invK + EPS);
.Lgm_p1p_loop:
	s_waitcnt lgkmcnt(4)
	v_mfma_f32_32x32x16_bf16 v[112:127], v[166:169], v[174:177], v[112:127]
	v_mfma_f32_32x32x16_bf16 v[96:111], v[166:169], v[178:181], v[96:111]
	v_mfma_f32_32x32x16_bf16 v[48:63], v[166:169], v[182:185], v[48:63]
	v_mfma_f32_32x32x16_bf16 v[32:47], v[166:169], v[186:189], v[32:47]
	v_mfma_f32_32x32x16_bf16 v[80:95], v[170:173], v[174:177], v[80:95]
	v_mfma_f32_32x32x16_bf16 v[64:79], v[170:173], v[178:181], v[64:79]
	v_mfma_f32_32x32x16_bf16 v[16:31], v[170:173], v[182:185], v[16:31]
	v_mfma_f32_32x32x16_bf16 v[0:15], v[170:173], v[186:189], v[0:15]
	s_setprio 0
	s_waitcnt vmcnt(8) lgkmcnt(0)
	s_barrier
	s_setprio 1
	v_mfma_f32_32x32x16_bf16 v[112:127], v[212:215], v[220:223], v[112:127]
	ds_read_b128 v[166:169], v190 offset:32768
	s_mov_b32 m0, s5
	v_lshl_add_u64 v[142:143], v[136:137], 0, s[20:21]
	global_load_lds_dwordx4 v[142:143], off
	v_mfma_f32_32x32x16_bf16 v[96:111], v[212:215], v[224:227], v[96:111]
	ds_read_b128 v[170:173], v190 offset:34816
	s_add_u32 m0, s5, 0x2000
	v_lshl_add_u64 v[148:149], v[130:131], 0, s[20:21]
	global_load_lds_dwordx4 v[148:149], off
	v_mfma_f32_32x32x16_bf16 v[48:63], v[212:215], v[228:231], v[48:63]
	ds_read_b128 v[174:177], v191 offset:49152
	s_add_u32 m0, s5, 0x4000
	v_lshl_add_u64 v[142:143], v[140:141], 0, s[20:21]
	global_load_lds_dwordx4 v[142:143], off
	v_mfma_f32_32x32x16_bf16 v[32:47], v[212:215], v[232:235], v[32:47]
	ds_read_b128 v[178:181], v191 offset:51200
	s_add_u32 m0, s5, 0x6000
	v_lshl_add_u64 v[148:149], v[138:139], 0, s[20:21]
	global_load_lds_dwordx4 v[148:149], off
	ds_read_b128 v[212:215], v132 offset:32768
	s_add_u32 s20, s20, 64
	s_addc_u32 s21, s21, 0
	v_mfma_f32_32x32x16_bf16 v[80:95], v[216:219], v[220:223], v[80:95]
	ds_read_b128 v[182:185], v191 offset:53248
	ds_read_b128 v[220:223], v165 offset:49152
	v_mfma_f32_32x32x16_bf16 v[64:79], v[216:219], v[224:227], v[64:79]
	ds_read_b128 v[186:189], v191 offset:55296
	ds_read_b128 v[224:227], v165 offset:51200
	v_mfma_f32_32x32x16_bf16 v[16:31], v[216:219], v[228:231], v[16:31]
	ds_read_b128 v[228:231], v165 offset:53248
	v_mfma_f32_32x32x16_bf16 v[0:15], v[216:219], v[232:235], v[0:15]
	ds_read_b128 v[232:235], v165 offset:55296
	ds_read_b128 v[216:219], v132 offset:34816
	v_xor_b32_e32 v190, 0x10000, v190
	v_xor_b32_e32 v191, 0x10000, v191
	v_xor_b32_e32 v132, 0x10000, v132
	v_xor_b32_e32 v165, 0x10000, v165
	s_waitcnt lgkmcnt(4)
	v_mfma_f32_32x32x16_bf16 v[112:127], v[166:169], v[174:177], v[112:127]
	v_mfma_f32_32x32x16_bf16 v[96:111], v[166:169], v[178:181], v[96:111]
	v_mfma_f32_32x32x16_bf16 v[48:63], v[166:169], v[182:185], v[48:63]
	v_mfma_f32_32x32x16_bf16 v[32:47], v[166:169], v[186:189], v[32:47]
	v_mfma_f32_32x32x16_bf16 v[80:95], v[170:173], v[174:177], v[80:95]
	v_mfma_f32_32x32x16_bf16 v[64:79], v[170:173], v[178:181], v[64:79]
	v_mfma_f32_32x32x16_bf16 v[16:31], v[170:173], v[182:185], v[16:31]
	v_mfma_f32_32x32x16_bf16 v[0:15], v[170:173], v[186:189], v[0:15]
	s_setprio 0
	s_waitcnt vmcnt(8) lgkmcnt(0)
	s_barrier
	s_setprio 1
	v_mfma_f32_32x32x16_bf16 v[112:127], v[212:215], v[220:223], v[112:127]
	ds_read_b128 v[166:169], v190
	s_add_u32 m0, s5, 0x8000
	v_lshl_add_u64 v[142:143], v[136:137], 0, s[20:21]
	global_load_lds_dwordx4 v[142:143], off
	v_mfma_f32_32x32x16_bf16 v[96:111], v[212:215], v[224:227], v[96:111]
	ds_read_b128 v[170:173], v190 offset:2048
	s_add_u32 m0, s5, 0xa000
	v_lshl_add_u64 v[148:149], v[130:131], 0, s[20:21]
	global_load_lds_dwordx4 v[148:149], off
	v_mfma_f32_32x32x16_bf16 v[48:63], v[212:215], v[228:231], v[48:63]
	ds_read_b128 v[174:177], v191 offset:16384
	s_add_u32 m0, s5, 0xc000
	v_lshl_add_u64 v[142:143], v[140:141], 0, s[20:21]
	global_load_lds_dwordx4 v[142:143], off
	v_mfma_f32_32x32x16_bf16 v[32:47], v[212:215], v[232:235], v[32:47]
	ds_read_b128 v[178:181], v191 offset:18432
	s_add_u32 m0, s5, 0xe000
	v_lshl_add_u64 v[148:149], v[138:139], 0, s[20:21]
	global_load_lds_dwordx4 v[148:149], off
	ds_read_b128 v[212:215], v132
	s_add_u32 s20, s20, 64
	s_addc_u32 s21, s21, 0
	v_mfma_f32_32x32x16_bf16 v[80:95], v[216:219], v[220:223], v[80:95]
	ds_read_b128 v[182:185], v191 offset:20480
	ds_read_b128 v[220:223], v165 offset:16384
	v_mfma_f32_32x32x16_bf16 v[64:79], v[216:219], v[224:227], v[64:79]
	ds_read_b128 v[186:189], v191 offset:22528
	ds_read_b128 v[224:227], v165 offset:18432
	v_mfma_f32_32x32x16_bf16 v[16:31], v[216:219], v[228:231], v[16:31]
	ds_read_b128 v[228:231], v165 offset:20480
	v_mfma_f32_32x32x16_bf16 v[0:15], v[216:219], v[232:235], v[0:15]
	ds_read_b128 v[232:235], v165 offset:22528
	ds_read_b128 v[216:219], v132 offset:2048
	s_xor_b32 s5, s5, 0x10000
	s_add_u32 s2, s2, 0x80
	s_cmpk_lg_i32 s2, 0x1000
	s_setprio 0
	s_cbranch_scc1 .Lgm_p1p_loop
	s_waitcnt lgkmcnt(0)
	s_mov_b64 s[20:21], 0xc0
	s_waitcnt vmcnt(0)
	s_waitcnt vmcnt(0)
	s_barrier
	s_and_saveexec_b64 s[2:3], vcc
	s_cbranch_execz .LBB0_241
	v_mul_f32_e32 v130, 0x4b800000, v135
	v_cmp_gt_f32_e32 vcc, s24, v135
	v_lshl_add_u32 v131, v128, 2, 0
	v_add_u32_e32 v131, 0x12000, v131
	v_cndmask_b32_e32 v130, v135, v130, vcc
	v_rsq_f32_e32 v130, v130
	s_nop 0
	v_mul_f32_e32 v132, 0x45800000, v130
	v_cndmask_b32_e32 v130, v130, v132, vcc
	ds_write_b32 v131, v130

; #define MFMA32(a, b, c) __builtin_amdgcn_mfma_f32_32x32x16_bf16((a), (b), (c), 0, 0, 0)
; DI void gemm_mainloop(const bf16_t* __restrict__ A, int lda, const bf16_t* __restrict__ B, int ldb, int K,
;                       f32x16 (&acc)[2][4], char* smem, const int tid) {
;     ...
;   for (int kt = 0; kt < nk; ++kt) {
;     asm volatile("s_waitcnt vmcnt(8) lgkmcnt(0)" ::: "memory");
;     __builtin_amdgcn_s_barrier();
;     dma_stage(A, lda, B, ldb, (kt + 3) * 32, smem + ((kt + 3) & 3) * STG, w, lane);
;     const char* st = smem + (kt & 3) * STG;
;     _Pragma("unroll") for (int ks = 0; ks < 2; ++ks) {
;       const int oo = ks ? o1 : o0;
;       bf16x8 a0 = *(const bf16x8*)(st + aoff + oo);
;       bf16x8 a1 = *(const bf16x8*)(st + aoff + 32 * 64 + oo);
;       bf16x8 b0 = *(const bf16x8*)(st + boff + oo);
;       bf16x8 b1 = *(const bf16x8*)(st + boff + 32 * 64 + oo);
;       bf16x8 b2 = *(const bf16x8*)(st + boff + 64 * 64 + oo);
;       bf16x8 b3 = *(const bf16x8*)(st + boff + 96 * 64 + oo);
;       acc[0][0] = MFMA32(a0, b0, acc[0][0]); acc[0][1] = MFMA32(a0, b1, acc[0][1]);
;       acc[0][2] = MFMA32(a0, b2, acc[0][2]); acc[0][3] = MFMA32(a0, b3, acc[0][3]);
;       acc[1][0] = MFMA32(a1, b0, acc[1][0]); acc[1][1] = MFMA32(a1, b1, acc[1][1]);
;       acc[1][2] = MFMA32(a1, b2, acc[1][2]); acc[1][3] = MFMA32(a1, b3, acc[1][3]);
;     }
.Lgm_p5o_loop:
	s_waitcnt lgkmcnt(4)
	v_mfma_f32_32x32x16_bf16 v[112:127], v[170:173], v[178:181], v[112:127]
	v_mfma_f32_32x32x16_bf16 v[96:111], v[170:173], v[182:185], v[96:111]
	v_mfma_f32_32x32x16_bf16 v[48:63], v[170:173], v[186:189], v[48:63]
	v_mfma_f32_32x32x16_bf16 v[32:47], v[170:173], v[190:193], v[32:47]
	v_mfma_f32_32x32x16_bf16 v[80:95], v[174:177], v[178:181], v[80:95]
	v_mfma_f32_32x32x16_bf16 v[64:79], v[174:177], v[182:185], v[64:79]
	v_mfma_f32_32x32x16_bf16 v[16:31], v[174:177], v[186:189], v[16:31]
	v_mfma_f32_32x32x16_bf16 v[0:15], v[174:177], v[190:193], v[0:15]
	s_setprio 0
	s_waitcnt vmcnt(8) lgkmcnt(0)
	s_barrier
	s_setprio 1
	v_mfma_f32_32x32x16_bf16 v[112:127], v[212:215], v[220:223], v[112:127]
	ds_read_b128 v[170:173], v195 offset:32768
	s_mov_b32 m0, s17
	v_lshl_add_u64 v[136:137], v[130:131], 0, s[24:25]
	global_load_lds_dwordx4 v[136:137], off
	v_mfma_f32_32x32x16_bf16 v[96:111], v[212:215], v[224:227], v[96:111]
	ds_read_b128 v[174:177], v195 offset:34816
	s_add_u32 m0, s17, 0x2000
	v_lshl_add_u64 v[138:139], v[128:129], 0, s[24:25]
	global_load_lds_dwordx4 v[138:139], off
	v_mfma_f32_32x32x16_bf16 v[48:63], v[212:215], v[228:231], v[48:63]
	ds_read_b128 v[178:181], v196 offset:49152
	s_add_u32 m0, s17, 0x4000
	v_lshl_add_u64 v[136:137], v[134:135], 0, s[24:25]
	global_load_lds_dwordx4 v[136:137], off
	v_mfma_f32_32x32x16_bf16 v[32:47], v[212:215], v[232:235], v[32:47]
	ds_read_b128 v[182:185], v196 offset:51200
	s_add_u32 m0, s17, 0x6000
	v_lshl_add_u64 v[138:139], v[132:133], 0, s[24:25]
	global_load_lds_dwordx4 v[138:139], off
	ds_read_b128 v[212:215], v152 offset:32768
	s_add_u32 s24, s24, 64
	s_addc_u32 s25, s25, 0
	v_mfma_f32_32x32x16_bf16 v[80:95], v[216:219], v[220:223], v[80:95]
	ds_read_b128 v[186:189], v196 offset:53248
	ds_read_b128 v[220:223], v194 offset:49152
	v_mfma_f32_32x32x16_bf16 v[64:79], v[216:219], v[224:227], v[64:79]
	ds_read_b128 v[190:193], v196 offset:55296
	ds_read_b128 v[224:227], v194 offset:51200
	v_mfma_f32_32x32x16_bf16 v[16:31], v[216:219], v[228:231], v[16:31]
	ds_read_b128 v[228:231], v194 offset:53248
	v_mfma_f32_32x32x16_bf16 v[0:15], v[216:219], v[232:235], v[0:15]
	ds_read_b128 v[232:235], v194 offset:55296
	ds_read_b128 v[216:219], v152 offset:34816
	v_xor_b32_e32 v195, 0x10000, v195
	v_xor_b32_e32 v196, 0x10000, v196
	v_xor_b32_e32 v152, 0x10000, v152
	v_xor_b32_e32 v194, 0x10000, v194
	s_waitcnt lgkmcnt(4)
	v_mfma_f32_32x32x16_bf16 v[112:127], v[170:173], v[178:181], v[112:127]
	v_mfma_f32_32x32x16_bf16 v[96:111], v[170:173], v[182:185], v[96:111]
	v_mfma_f32_32x32x16_bf16 v[48:63], v[170:173], v[186:189], v[48:63]
	v_mfma_f32_32x32x16_bf16 v[32:47], v[170:173], v[190:193], v[32:47]
	v_mfma_f32_32x32x16_bf16 v[80:95], v[174:177], v[178:181], v[80:95]
	v_mfma_f32_32x32x16_bf16 v[64:79], v[174:177], v[182:185], v[64:79]
	v_mfma_f32_32x32x16_bf16 v[16:31], v[174:177], v[186:189], v[16:31]
	v_mfma_f32_32x32x16_bf16 v[0:15], v[174:177], v[190:193], v[0:15]
	s_setprio 0
	s_waitcnt vmcnt(8) lgkmcnt(0)
	s_barrier
	s_setprio 1
	v_mfma_f32_32x32x16_bf16 v[112:127], v[212:215], v[220:223], v[112:127]
	ds_read_b128 v[170:173], v195
	s_add_u32 m0, s17, 0x8000
	v_lshl_add_u64 v[136:137], v[130:131], 0, s[24:25]
	global_load_lds_dwordx4 v[136:137], off
	v_mfma_f32_32x32x16_bf16 v[96:111], v[212:215], v[224:227], v[96:111]
	ds_read_b128 v[174:177], v195 offset:2048
	s_add_u32 m0, s17, 0xa000
	v_lshl_add_u64 v[138:139], v[128:129], 0, s[24:25]
	global_load_lds_dwordx4 v[138:139], off
	v_mfma_f32_32x32x16_bf16 v[48:63], v[212:215], v[228:231], v[48:63]
	ds_read_b128 v[178:181], v196 offset:16384
	s_add_u32 m0, s17, 0xc000
	v_lshl_add_u64 v[136:137], v[134:135], 0, s[24:25]
	global_load_lds_dwordx4 v[136:137], off
	v_mfma_f32_32x32x16_bf16 v[32:47], v[212:215], v[232:235], v[32:47]
	ds_read_b128 v[182:185], v196 offset:18432
	s_add_u32 m0, s17, 0xe000
	v_lshl_add_u64 v[138:139], v[132:133], 0, s[24:25]
	global_load_lds_dwordx4 v[138:139], off
	ds_read_b128 v[212:215], v152
	s_add_u32 s24, s24, 64
	s_addc_u32 s25, s25, 0
	v_mfma_f32_32x32x16_bf16 v[80:95], v[216:219], v[220:223], v[80:95]
	ds_read_b128 v[186:189], v196 offset:20480
	ds_read_b128 v[220:223], v194 offset:16384
	v_mfma_f32_32x32x16_bf16 v[64:79], v[216:219], v[224:227], v[64:79]
	ds_read_b128 v[190:193], v196 offset:22528
	ds_read_b128 v[224:227], v194 offset:18432
	v_mfma_f32_32x32x16_bf16 v[16:31], v[216:219], v[228:231], v[16:31]
	ds_read_b128 v[228:231], v194 offset:20480
	v_mfma_f32_32x32x16_bf16 v[0:15], v[216:219], v[232:235], v[0:15]
	ds_read_b128 v[232:235], v194 offset:22528
	ds_read_b128 v[216:219], v152 offset:2048
	s_xor_b32 s17, s17, 0x10000
	s_add_u32 s2, s2, 0x80
	s_cmpk_lg_i32 s2, 0x1000
	s_setprio 0
	s_cbranch_scc1 .Lgm_p5o_loop
; DI float red8(float s) { s += __shfl_xor(s, 1); s += __shfl_xor(s, 2); s += __shfl_xor(s, 4); return s; }
; DI void p5_tile(const Params& P, int l, int half, int t, char* smem) {
;     ...
;   _Pragma("unroll") for (int seg = 0; seg < 2; ++seg) {
;     const int gc = n0 + wn * 128 + seg * 64 + ch * 8;
;     _Pragma("unroll") for (int mi = 0; mi < 2; ++mi) {
;       stage_block(acc[mi][2 * seg], acc[mi][2 * seg + 1], sE, r, h);
;       _Pragma("unroll") for (int ps = 0; ps < 4; ++ps) {
;         const int rr = ps * 8 + (lane >> 3);
;         const int m = m0 + wm * 64 + mi * 32 + rr;
;         const size_t off = (size_t)m * DM + gc;
;         float v[8]; read8(sE + rr * EST + ch * 8, v);
;         float x[8]; read8(xin + off, x);
;         _Pragma("unroll") for (int j = 0; j < 8; ++j) v[j] += x[j];
;         *(float4*)(xo + off) = make_float4(v[0], v[1], v[2], v[3]);
;         *(float4*)(xo + off + 4) = make_float4(v[4], v[5], v[6], v[7]);
;         if (l < DEPTH - 1) {
;           *(u32x4*)(xbo + off) = pack8u(v);
;           float sq = red8(sum8sq(v));
;           if (ch == 0) sqn[(size_t)m * 32 + ((n0 + wn * 128 + seg * 64) >> 6)] = sq;
;         }
	s_waitcnt lgkmcnt(0)
	s_mov_b64 s[24:25], 0xc0
	s_movk_i32 s1, 0x2200
	v_mul_lo_u32 v128, v159, s1
	v_mul_u32_u24_e32 v129, 0x110, v158
	v_add_u32_e32 v130, 0, v128
	v_lshlrev_b32_e32 v129, 2, v129
	v_lshlrev_b32_e32 v132, 2, v156
	v_add3_u32 v134, v130, v129, v132
	v_add3_u32 v135, v130, v132, v129
	v_and_b32_e32 v131, 7, v157
	v_lshrrev_b32_e32 v129, 3, v154
	v_add_u32_e32 v143, s0, v155
	v_add_u32_e32 v136, 0x800, v134
	v_add_u32_e32 v137, 0x800, v135
	v_add_u32_e32 v140, 0x1000, v135
	s_waitcnt vmcnt(0)
	s_waitcnt vmcnt(0)
	s_barrier
	v_or_b32_e32 v128, s16, v160
	v_lshlrev_b32_e32 v152, 3, v131
	ds_write2_b32 v134, v112, v113 offset1:68
	ds_write2_b32 v135, v96, v97 offset0:32 offset1:100
	ds_write2_b32 v134, v114, v115 offset0:136 offset1:204
	ds_write2_b32 v135, v98, v99 offset0:168 offset1:236
	ds_write2_b32 v136, v116, v117 offset0:32 offset1:100
	ds_write2_b32 v137, v100, v101 offset0:64 offset1:132
	ds_write2_b32 v136, v118, v119 offset0:168 offset1:236
	ds_write2_b32 v140, v104, v105 offset0:96 offset1:164
	v_or_b32_e32 v104, v143, v129
	v_or_b32_e32 v132, v128, v152
	v_add_u32_e32 v141, 0x1200, v134
	v_ashrrev_i32_e32 v105, 31, v104
	v_ashrrev_i32_e32 v133, 31, v132
	ds_write2_b32 v141, v122, v123 offset0:72 offset1:140
	v_add_u32_e32 v123, 0x1200, v135
	v_add_u32_e32 v142, 0x1800, v134
	v_lshlrev_b64 v[112:113], 11, v[104:105]
	ds_write2_b32 v123, v106, v107 offset0:104 offset1:172
	ds_write2_b32 v142, v124, v125 offset0:96 offset1:164
	v_add_u32_e32 v125, 0x1a00, v134
	v_lshl_add_u64 v[106:107], v[112:113], 0, v[132:133]
	v_lshl_add_u32 v154, v131, 5, v130
	v_add_u32_e32 v138, 0xa00, v135
	v_add_u32_e32 v139, 0x1000, v134
	v_add_u32_e32 v124, 0x1800, v135
	ds_write2_b32 v125, v126, v127 offset0:104 offset1:172
	v_add_u32_e32 v126, 0x1c00, v135
	s_movk_i32 s2, 0x110
	v_lshlrev_b64 v[118:119], 2, v[106:107]
	ds_write2_b32 v138, v102, v103 offset0:72 offset1:140
	ds_write2_b32 v139, v120, v121 offset0:64 offset1:132
	ds_write2_b32 v124, v108, v109 offset0:128 offset1:196
	ds_write2_b32 v126, v110, v111 offset0:8 offset1:76
	v_mad_u32_u24 v102, v129, s2, v154
	v_lshl_add_u64 v[100:101], s[8:9], 0, v[118:119]
	ds_read_b128 v[96:99], v102
	ds_read_b128 v[108:111], v102 offset:16
	global_load_dwordx4 v[114:117], v[100:101], off offset:16
	s_nop 0
	global_load_dwordx4 v[100:103], v[100:101], off
	v_ashrrev_i32_e32 v130, 6, v128
	v_cmp_eq_u32_e64 s[0:1], 0, v131
	v_ashrrev_i32_e32 v131, 31, v130
	v_lshl_add_u64 v[130:131], v[130:131], 2, s[12:13]
	s_andn2_b64 vcc, exec, s[14:15]
	s_waitcnt vmcnt(0) lgkmcnt(1)
	v_pk_add_f32 v[100:101], v[96:97], v[100:101]
	v_pk_add_f32 v[102:103], v[98:99], v[102:103]
	s_waitcnt lgkmcnt(0)
	v_pk_add_f32 v[96:97], v[108:109], v[114:115]
	v_lshl_add_u64 v[108:109], s[6:7], 0, v[118:119]
	v_pk_add_f32 v[98:99], v[110:111], v[116:117]
	global_store_dwordx4 v[108:109], v[100:103], off
	global_store_dwordx4 v[108:109], v[96:99], off offset:16
	v_cndmask_b32_e64 v108, 0, 1, s[14:15]
	v_cmp_ne_u32_e64 s[2:3], 1, v108
	s_cbranch_vccnz .LBB0_666
	v_cvt_pk_bf16_f32 v108, v100, v101
	v_pk_mul_f32 v[100:101], v[100:101], v[100:101]
	v_cvt_pk_bf16_f32 v109, v102, v103
	v_pk_mul_f32 v[102:103], v[102:103], v[102:103]
	v_add_f32_e32 v100, v100, v101
	v_add_f32_e32 v100, v102, v100
	v_cvt_pk_bf16_f32 v110, v96, v97
	v_pk_mul_f32 v[96:97], v[96:97], v[96:97]
	v_add_f32_e32 v100, v103, v100
	v_add_f32_e32 v96, v96, v100
	v_add_f32_e32 v96, v97, v96
	v_xor_b32_e32 v97, 1, v145
	v_cvt_pk_bf16_f32 v111, v98, v99
	v_pk_mul_f32 v[98:99], v[98:99], v[98:99]
	v_cmp_lt_i32_e32 vcc, v97, v198
	v_add_f32_e32 v96, v98, v96
	v_add_f32_e32 v96, v99, v96
	v_cndmask_b32_e32 v97, v145, v97, vcc
	v_lshlrev_b32_e32 v97, 2, v97
	ds_bpermute_b32 v97, v97, v96
	v_lshl_add_u64 v[106:107], v[106:107], 1, s[10:11]
	global_store_dwordx4 v[106:107], v[108:111], off
	s_waitcnt lgkmcnt(0)
	v_add_f32_e32 v96, v96, v97
	v_xor_b32_e32 v97, 2, v145
	v_cmp_lt_i32_e32 vcc, v97, v198
	s_nop 1
	v_cndmask_b32_e32 v97, v145, v97, vcc
	v_lshlrev_b32_e32 v97, 2, v97
	ds_bpermute_b32 v97, v97, v96
	s_waitcnt lgkmcnt(0)
	v_add_f32_e32 v96, v96, v97
	v_xor_b32_e32 v97, 4, v145
	v_cmp_lt_i32_e32 vcc, v97, v198
	s_nop 1
	v_cndmask_b32_e32 v97, v145, v97, vcc
	v_lshlrev_b32_e32 v97, 2, v97
	ds_bpermute_b32 v97, v97, v96
	s_and_saveexec_b64 s[16:17], s[0:1]
	s_cbranch_execz .LBB0_665
	s_waitcnt lgkmcnt(0)
	v_add_f32_e32 v98, v96, v97
	v_lshlrev_b64 v[96:97], 7, v[104:105]
	v_lshl_add_u64 v[96:97], v[130:131], 0, v[96:97]
	global_store_dword v[96:97], v98, off

; #define MFMA32(a, b, c) __builtin_amdgcn_mfma_f32_32x32x16_bf16((a), (b), (c), 0, 0, 0)
; DI void gemm_mainloop(const bf16_t* __restrict__ A, int lda, const bf16_t* __restrict__ B, int ldb, int K,
;                       f32x16 (&acc)[2][4], char* smem, const int tid) {
;     ...
;   for (int kt = 0; kt < nk; ++kt) {
;     asm volatile("s_waitcnt vmcnt(8) lgkmcnt(0)" ::: "memory");
;     __builtin_amdgcn_s_barrier();
;     dma_stage(A, lda, B, ldb, (kt + 3) * 32, smem + ((kt + 3) & 3) * STG, w, lane);
;     const char* st = smem + (kt & 3) * STG;
;     _Pragma("unroll") for (int ks = 0; ks < 2; ++ks) {
;       const int oo = ks ? o1 : o0;
;       bf16x8 a0 = *(const bf16x8*)(st + aoff + oo);
;       bf16x8 a1 = *(const bf16x8*)(st + aoff + 32 * 64 + oo);
;       bf16x8 b0 = *(const bf16x8*)(st + boff + oo);
;       bf16x8 b1 = *(const bf16x8*)(st + boff + 32 * 64 + oo);
;       bf16x8 b2 = *(const bf16x8*)(st + boff + 64 * 64 + oo);
;       bf16x8 b3 = *(const bf16x8*)(st + boff + 96 * 64 + oo);
;       acc[0][0] = MFMA32(a0, b0, acc[0][0]); acc[0][1] = MFMA32(a0, b1, acc[0][1]);
;       acc[0][2] = MFMA32(a0, b2, acc[0][2]); acc[0][3] = MFMA32(a0, b3, acc[0][3]);
;       acc[1][0] = MFMA32(a1, b0, acc[1][0]); acc[1][1] = MFMA32(a1, b1, acc[1][1]);
;       acc[1][2] = MFMA32(a1, b2, acc[1][2]); acc[1][3] = MFMA32(a1, b3, acc[1][3]);
;     }
.Lgm_p5e_loop:
	s_waitcnt lgkmcnt(4)
	v_mfma_f32_32x32x16_bf16 v[112:127], v[170:173], v[178:181], v[112:127]
	v_mfma_f32_32x32x16_bf16 v[96:111], v[170:173], v[182:185], v[96:111]
	v_mfma_f32_32x32x16_bf16 v[48:63], v[170:173], v[186:189], v[48:63]
	v_mfma_f32_32x32x16_bf16 v[32:47], v[170:173], v[190:193], v[32:47]
	v_mfma_f32_32x32x16_bf16 v[80:95], v[174:177], v[178:181], v[80:95]
	v_mfma_f32_32x32x16_bf16 v[64:79], v[174:177], v[182:185], v[64:79]
	v_mfma_f32_32x32x16_bf16 v[16:31], v[174:177], v[186:189], v[16:31]
	v_mfma_f32_32x32x16_bf16 v[0:15], v[174:177], v[190:193], v[0:15]
	s_setprio 0
	s_waitcnt vmcnt(8) lgkmcnt(0)
	s_barrier
	s_setprio 1
	v_mfma_f32_32x32x16_bf16 v[112:127], v[212:215], v[220:223], v[112:127]
	ds_read_b128 v[170:173], v195 offset:32768
	s_mov_b32 m0, s15
	v_lshl_add_u64 v[136:137], v[130:131], 0, s[24:25]
	global_load_lds_dwordx4 v[136:137], off
	v_mfma_f32_32x32x16_bf16 v[96:111], v[212:215], v[224:227], v[96:111]
	ds_read_b128 v[174:177], v195 offset:34816
	s_add_u32 m0, s15, 0x2000
	v_lshl_add_u64 v[138:139], v[128:129], 0, s[24:25]
	global_load_lds_dwordx4 v[138:139], off
	v_mfma_f32_32x32x16_bf16 v[48:63], v[212:215], v[228:231], v[48:63]
	ds_read_b128 v[178:181], v196 offset:49152
	s_add_u32 m0, s15, 0x4000
	v_lshl_add_u64 v[136:137], v[134:135], 0, s[24:25]
	global_load_lds_dwordx4 v[136:137], off
	v_mfma_f32_32x32x16_bf16 v[32:47], v[212:215], v[232:235], v[32:47]
	ds_read_b128 v[182:185], v196 offset:51200
	s_add_u32 m0, s15, 0x6000
	v_lshl_add_u64 v[138:139], v[132:133], 0, s[24:25]
	global_load_lds_dwordx4 v[138:139], off
	ds_read_b128 v[212:215], v152 offset:32768
	s_add_u32 s24, s24, 64
	s_addc_u32 s25, s25, 0
	v_mfma_f32_32x32x16_bf16 v[80:95], v[216:219], v[220:223], v[80:95]
	ds_read_b128 v[186:189], v196 offset:53248
	ds_read_b128 v[220:223], v194 offset:49152
	v_mfma_f32_32x32x16_bf16 v[64:79], v[216:219], v[224:227], v[64:79]
	ds_read_b128 v[190:193], v196 offset:55296
	ds_read_b128 v[224:227], v194 offset:51200
	v_mfma_f32_32x32x16_bf16 v[16:31], v[216:219], v[228:231], v[16:31]
	ds_read_b128 v[228:231], v194 offset:53248
	v_mfma_f32_32x32x16_bf16 v[0:15], v[216:219], v[232:235], v[0:15]
	ds_read_b128 v[232:235], v194 offset:55296
	ds_read_b128 v[216:219], v152 offset:34816
	v_xor_b32_e32 v195, 0x10000, v195
	v_xor_b32_e32 v196, 0x10000, v196
	v_xor_b32_e32 v152, 0x10000, v152
	v_xor_b32_e32 v194, 0x10000, v194
	s_waitcnt lgkmcnt(4)
	v_mfma_f32_32x32x16_bf16 v[112:127], v[170:173], v[178:181], v[112:127]
	v_mfma_f32_32x32x16_bf16 v[96:111], v[170:173], v[182:185], v[96:111]
	v_mfma_f32_32x32x16_bf16 v[48:63], v[170:173], v[186:189], v[48:63]
	v_mfma_f32_32x32x16_bf16 v[32:47], v[170:173], v[190:193], v[32:47]
	v_mfma_f32_32x32x16_bf16 v[80:95], v[174:177], v[178:181], v[80:95]
	v_mfma_f32_32x32x16_bf16 v[64:79], v[174:177], v[182:185], v[64:79]
	v_mfma_f32_32x32x16_bf16 v[16:31], v[174:177], v[186:189], v[16:31]
	v_mfma_f32_32x32x16_bf16 v[0:15], v[174:177], v[190:193], v[0:15]
	s_setprio 0
	s_waitcnt vmcnt(8) lgkmcnt(0)
	s_barrier
	s_setprio 1
	v_mfma_f32_32x32x16_bf16 v[112:127], v[212:215], v[220:223], v[112:127]
	ds_read_b128 v[170:173], v195
	s_add_u32 m0, s15, 0x8000
	v_lshl_add_u64 v[136:137], v[130:131], 0, s[24:25]
	global_load_lds_dwordx4 v[136:137], off
	v_mfma_f32_32x32x16_bf16 v[96:111], v[212:215], v[224:227], v[96:111]
	ds_read_b128 v[174:177], v195 offset:2048
	s_add_u32 m0, s15, 0xa000
	v_lshl_add_u64 v[138:139], v[128:129], 0, s[24:25]
	global_load_lds_dwordx4 v[138:139], off
	v_mfma_f32_32x32x16_bf16 v[48:63], v[212:215], v[228:231], v[48:63]
	ds_read_b128 v[178:181], v196 offset:16384
	s_add_u32 m0, s15, 0xc000
	v_lshl_add_u64 v[136:137], v[134:135], 0, s[24:25]
	global_load_lds_dwordx4 v[136:137], off
	v_mfma_f32_32x32x16_bf16 v[32:47], v[212:215], v[232:235], v[32:47]
	ds_read_b128 v[182:185], v196 offset:18432
	s_add_u32 m0, s15, 0xe000
	v_lshl_add_u64 v[138:139], v[132:133], 0, s[24:25]
	global_load_lds_dwordx4 v[138:139], off
	ds_read_b128 v[212:215], v152
	s_add_u32 s24, s24, 64
	s_addc_u32 s25, s25, 0
	v_mfma_f32_32x32x16_bf16 v[80:95], v[216:219], v[220:223], v[80:95]
	ds_read_b128 v[186:189], v196 offset:20480
	ds_read_b128 v[220:223], v194 offset:16384
	v_mfma_f32_32x32x16_bf16 v[64:79], v[216:219], v[224:227], v[64:79]
	ds_read_b128 v[190:193], v196 offset:22528
	ds_read_b128 v[224:227], v194 offset:18432
	v_mfma_f32_32x32x16_bf16 v[16:31], v[216:219], v[228:231], v[16:31]
	ds_read_b128 v[228:231], v194 offset:20480
	v_mfma_f32_32x32x16_bf16 v[0:15], v[216:219], v[232:235], v[0:15]
	ds_read_b128 v[232:235], v194 offset:22528
	ds_read_b128 v[216:219], v152 offset:2048
	s_xor_b32 s15, s15, 0x10000
	s_add_u32 s2, s2, 0x80
	s_cmpk_lg_i32 s2, 0x1000
	s_setprio 0
	s_cbranch_scc1 .Lgm_p5e_loop
; DI float red8(float s) { s += __shfl_xor(s, 1); s += __shfl_xor(s, 2); s += __shfl_xor(s, 4); return s; }
; DI void p5_tile(const Params& P, int l, int half, int t, char* smem) {
;     ...
;   _Pragma("unroll") for (int seg = 0; seg < 2; ++seg) {
;     const int gc = n0 + wn * 128 + seg * 64 + ch * 8;
;     _Pragma("unroll") for (int mi = 0; mi < 2; ++mi) {
;       stage_block(acc[mi][2 * seg], acc[mi][2 * seg + 1], sE, r, h);
;       _Pragma("unroll") for (int ps = 0; ps < 4; ++ps) {
;         const int rr = ps * 8 + (lane >> 3);
;         const int m = m0 + wm * 64 + mi * 32 + rr;
;         const size_t off = (size_t)m * DM + gc;
;         float v[8]; read8(sE + rr * EST + ch * 8, v);
;         float x[8]; read8(xin + off, x);
;         _Pragma("unroll") for (int j = 0; j < 8; ++j) v[j] += x[j];
;         *(float4*)(xo + off) = make_float4(v[0], v[1], v[2], v[3]);
;         *(float4*)(xo + off + 4) = make_float4(v[4], v[5], v[6], v[7]);
;         if (l < DEPTH - 1) {
;           *(u32x4*)(xbo + off) = pack8u(v);
;           float sq = red8(sum8sq(v));
;           if (ch == 0) sqn[(size_t)m * 32 + ((n0 + wn * 128 + seg * 64) >> 6)] = sq;
;         }
	s_waitcnt lgkmcnt(0)
	s_mov_b64 s[24:25], 0xc0
	s_movk_i32 s1, 0x2200
	v_mul_lo_u32 v128, v159, s1
	v_mul_u32_u24_e32 v129, 0x110, v158
	v_add_u32_e32 v130, 0, v128
	v_lshlrev_b32_e32 v129, 2, v129
	v_lshlrev_b32_e32 v132, 2, v156
	v_add3_u32 v134, v130, v129, v132
	v_add3_u32 v135, v130, v132, v129
	v_and_b32_e32 v131, 7, v157
	v_lshrrev_b32_e32 v129, 3, v154
	v_add_u32_e32 v143, s0, v155
	v_add_u32_e32 v136, 0x800, v134
	v_add_u32_e32 v137, 0x800, v135
	v_add_u32_e32 v140, 0x1000, v135
	s_waitcnt vmcnt(0)
	s_waitcnt vmcnt(0)
	s_barrier
	v_or_b32_e32 v128, s14, v160
	v_lshlrev_b32_e32 v152, 3, v131
	ds_write2_b32 v134, v112, v113 offset1:68
	ds_write2_b32 v135, v96, v97 offset0:32 offset1:100
	ds_write2_b32 v134, v114, v115 offset0:136 offset1:204
	ds_write2_b32 v135, v98, v99 offset0:168 offset1:236
	ds_write2_b32 v136, v116, v117 offset0:32 offset1:100
	ds_write2_b32 v137, v100, v101 offset0:64 offset1:132
	ds_write2_b32 v136, v118, v119 offset0:168 offset1:236
	ds_write2_b32 v140, v104, v105 offset0:96 offset1:164
	v_or_b32_e32 v104, v143, v129
	v_or_b32_e32 v132, v128, v152
	v_add_u32_e32 v141, 0x1200, v134
	v_ashrrev_i32_e32 v105, 31, v104
	v_ashrrev_i32_e32 v133, 31, v132
	ds_write2_b32 v141, v122, v123 offset0:72 offset1:140
	v_add_u32_e32 v123, 0x1200, v135
	v_add_u32_e32 v142, 0x1800, v134
	v_lshlrev_b64 v[112:113], 11, v[104:105]
	ds_write2_b32 v123, v106, v107 offset0:104 offset1:172
	ds_write2_b32 v142, v124, v125 offset0:96 offset1:164
	v_add_u32_e32 v125, 0x1a00, v134
	v_lshl_add_u64 v[106:107], v[112:113], 0, v[132:133]
	v_lshl_add_u32 v154, v131, 5, v130
	v_add_u32_e32 v138, 0xa00, v135
	v_add_u32_e32 v139, 0x1000, v134
	v_add_u32_e32 v124, 0x1800, v135
	ds_write2_b32 v125, v126, v127 offset0:104 offset1:172
	v_add_u32_e32 v126, 0x1c00, v135
	s_movk_i32 s2, 0x110
	v_lshlrev_b64 v[118:119], 2, v[106:107]
	ds_write2_b32 v138, v102, v103 offset0:72 offset1:140
	ds_write2_b32 v139, v120, v121 offset0:64 offset1:132
	ds_write2_b32 v124, v108, v109 offset0:128 offset1:196
	ds_write2_b32 v126, v110, v111 offset0:8 offset1:76
	v_mad_u32_u24 v102, v129, s2, v154
	v_lshl_add_u64 v[100:101], s[6:7], 0, v[118:119]
	ds_read_b128 v[96:99], v102
	ds_read_b128 v[108:111], v102 offset:16
	global_load_dwordx4 v[114:117], v[100:101], off offset:16
	s_nop 0
	global_load_dwordx4 v[100:103], v[100:101], off
	v_ashrrev_i32_e32 v130, 6, v128
	v_cmp_eq_u32_e64 s[0:1], 0, v131
	v_ashrrev_i32_e32 v131, 31, v130
	v_lshl_add_u64 v[130:131], v[130:131], 2, s[10:11]
	s_andn2_b64 vcc, exec, s[12:13]
	s_waitcnt vmcnt(0) lgkmcnt(1)
	v_pk_add_f32 v[100:101], v[96:97], v[100:101]
	v_pk_add_f32 v[102:103], v[98:99], v[102:103]
	s_waitcnt lgkmcnt(0)
	v_pk_add_f32 v[96:97], v[108:109], v[114:115]
	v_lshl_add_u64 v[108:109], s[4:5], 0, v[118:119]
	v_pk_add_f32 v[98:99], v[110:111], v[116:117]
	global_store_dwordx4 v[108:109], v[100:103], off
	global_store_dwordx4 v[108:109], v[96:99], off offset:16
	v_cndmask_b32_e64 v108, 0, 1, s[12:13]
	v_cmp_ne_u32_e64 s[2:3], 1, v108
	s_cbranch_vccnz .LBB0_757
	v_cvt_pk_bf16_f32 v108, v100, v101
	v_pk_mul_f32 v[100:101], v[100:101], v[100:101]
	v_cvt_pk_bf16_f32 v109, v102, v103
	v_pk_mul_f32 v[102:103], v[102:103], v[102:103]
	v_add_f32_e32 v100, v100, v101
	v_add_f32_e32 v100, v102, v100
	v_cvt_pk_bf16_f32 v110, v96, v97
	v_pk_mul_f32 v[96:97], v[96:97], v[96:97]
	v_add_f32_e32 v100, v103, v100
	v_add_f32_e32 v96, v96, v100
	v_add_f32_e32 v96, v97, v96
	v_xor_b32_e32 v97, 1, v145
	v_cvt_pk_bf16_f32 v111, v98, v99
	v_pk_mul_f32 v[98:99], v[98:99], v[98:99]
	v_cmp_lt_i32_e32 vcc, v97, v198
	v_add_f32_e32 v96, v98, v96
	v_add_f32_e32 v96, v99, v96
	v_cndmask_b32_e32 v97, v145, v97, vcc
	v_lshlrev_b32_e32 v97, 2, v97
	ds_bpermute_b32 v97, v97, v96
	v_lshl_add_u64 v[106:107], v[106:107], 1, s[8:9]
	global_store_dwordx4 v[106:107], v[108:111], off
	s_waitcnt lgkmcnt(0)
	v_add_f32_e32 v96, v96, v97
	v_xor_b32_e32 v97, 2, v145
	v_cmp_lt_i32_e32 vcc, v97, v198
	s_nop 1
	v_cndmask_b32_e32 v97, v145, v97, vcc
	v_lshlrev_b32_e32 v97, 2, v97
	ds_bpermute_b32 v97, v97, v96
	s_waitcnt lgkmcnt(0)
	v_add_f32_e32 v96, v96, v97
	v_xor_b32_e32 v97, 4, v145
	v_cmp_lt_i32_e32 vcc, v97, v198
	s_nop 1
	v_cndmask_b32_e32 v97, v145, v97, vcc
	v_lshlrev_b32_e32 v97, 2, v97
	ds_bpermute_b32 v97, v97, v96
	s_and_saveexec_b64 s[14:15], s[0:1]
	s_cbranch_execz .LBB0_756
	s_waitcnt lgkmcnt(0)
	v_add_f32_e32 v98, v96, v97
	v_lshlrev_b64 v[96:97], 7, v[104:105]
	v_lshl_add_u64 v[96:97], v[130:131], 0, v[96:97]
	global_store_dword v[96:97], v98, off

; #define MFMA32(a, b, c) __builtin_amdgcn_mfma_f32_32x32x16_bf16((a), (b), (c), 0, 0, 0)
; DI void gemm_mainloop(const bf16_t* __restrict__ A, int lda, const bf16_t* __restrict__ B, int ldb, int K,
;                       f32x16 (&acc)[2][4], char* smem, const int tid) {
;     ...
;   for (int kt = 0; kt < nk; ++kt) {
;     asm volatile("s_waitcnt vmcnt(8) lgkmcnt(0)" ::: "memory");
;     __builtin_amdgcn_s_barrier();
;     dma_stage(A, lda, B, ldb, (kt + 3) * 32, smem + ((kt + 3) & 3) * STG, w, lane);
;     const char* st = smem + (kt & 3) * STG;
;     _Pragma("unroll") for (int ks = 0; ks < 2; ++ks) {
;       const int oo = ks ? o1 : o0;
;       bf16x8 a0 = *(const bf16x8*)(st + aoff + oo);
;       bf16x8 a1 = *(const bf16x8*)(st + aoff + 32 * 64 + oo);
;       bf16x8 b0 = *(const bf16x8*)(st + boff + oo);
;       bf16x8 b1 = *(const bf16x8*)(st + boff + 32 * 64 + oo);
;       bf16x8 b2 = *(const bf16x8*)(st + boff + 64 * 64 + oo);
;       bf16x8 b3 = *(const bf16x8*)(st + boff + 96 * 64 + oo);
;       acc[0][0] = MFMA32(a0, b0, acc[0][0]); acc[0][1] = MFMA32(a0, b1, acc[0][1]);
;       acc[0][2] = MFMA32(a0, b2, acc[0][2]); acc[0][3] = MFMA32(a0, b3, acc[0][3]);
;       acc[1][0] = MFMA32(a1, b0, acc[1][0]); acc[1][1] = MFMA32(a1, b1, acc[1][1]);
;       acc[1][2] = MFMA32(a1, b2, acc[1][2]); acc[1][3] = MFMA32(a1, b3, acc[1][3]);
;     }
; DI void rstd_publish(float s, float invK, float* srstd, int tid) {
;   if (tid < 256) srstd[tid] = rsqrtf(s * invK + EPS);
.Lgm_p1m_loop:
	s_waitcnt lgkmcnt(4)
	v_mfma_f32_32x32x16_bf16 v[112:127], v[172:175], v[180:183], v[112:127]
	v_mfma_f32_32x32x16_bf16 v[96:111], v[172:175], v[184:187], v[96:111]
	v_mfma_f32_32x32x16_bf16 v[48:63], v[172:175], v[188:191], v[48:63]
	v_mfma_f32_32x32x16_bf16 v[32:47], v[172:175], v[192:195], v[32:47]
	v_mfma_f32_32x32x16_bf16 v[80:95], v[176:179], v[180:183], v[80:95]
	v_mfma_f32_32x32x16_bf16 v[64:79], v[176:179], v[184:187], v[64:79]
	v_mfma_f32_32x32x16_bf16 v[16:31], v[176:179], v[188:191], v[16:31]
	v_mfma_f32_32x32x16_bf16 v[0:15], v[176:179], v[192:195], v[0:15]
	s_setprio 0
	s_waitcnt vmcnt(8) lgkmcnt(0)
	s_barrier
	s_setprio 1
	v_mfma_f32_32x32x16_bf16 v[112:127], v[212:215], v[220:223], v[112:127]
	ds_read_b128 v[172:175], v196 offset:32768
	s_mov_b32 m0, s5
	v_lshl_add_u64 v[142:143], v[136:137], 0, s[8:9]
	global_load_lds_dwordx4 v[142:143], off
	v_mfma_f32_32x32x16_bf16 v[96:111], v[212:215], v[224:227], v[96:111]
	ds_read_b128 v[176:179], v196 offset:34816
	s_add_u32 m0, s5, 0x2000
	v_lshl_add_u64 v[154:155], v[130:131], 0, s[8:9]
	global_load_lds_dwordx4 v[154:155], off
	v_mfma_f32_32x32x16_bf16 v[48:63], v[212:215], v[228:231], v[48:63]
	ds_read_b128 v[180:183], v197 offset:49152
	s_add_u32 m0, s5, 0x4000
	v_lshl_add_u64 v[142:143], v[140:141], 0, s[8:9]
	global_load_lds_dwordx4 v[142:143], off
	v_mfma_f32_32x32x16_bf16 v[32:47], v[212:215], v[232:235], v[32:47]
	ds_read_b128 v[184:187], v197 offset:51200
	s_add_u32 m0, s5, 0x6000
	v_lshl_add_u64 v[154:155], v[138:139], 0, s[8:9]
	global_load_lds_dwordx4 v[154:155], off
	ds_read_b128 v[212:215], v152 offset:32768
	s_add_u32 s8, s8, 64
	s_addc_u32 s9, s9, 0
	v_mfma_f32_32x32x16_bf16 v[80:95], v[216:219], v[220:223], v[80:95]
	ds_read_b128 v[188:191], v197 offset:53248
	ds_read_b128 v[220:223], v171 offset:49152
	v_mfma_f32_32x32x16_bf16 v[64:79], v[216:219], v[224:227], v[64:79]
	ds_read_b128 v[192:195], v197 offset:55296
	ds_read_b128 v[224:227], v171 offset:51200
	v_mfma_f32_32x32x16_bf16 v[16:31], v[216:219], v[228:231], v[16:31]
	ds_read_b128 v[228:231], v171 offset:53248
	v_mfma_f32_32x32x16_bf16 v[0:15], v[216:219], v[232:235], v[0:15]
	ds_read_b128 v[232:235], v171 offset:55296
	ds_read_b128 v[216:219], v152 offset:34816
	v_xor_b32_e32 v196, 0x10000, v196
	v_xor_b32_e32 v197, 0x10000, v197
	v_xor_b32_e32 v152, 0x10000, v152
	v_xor_b32_e32 v171, 0x10000, v171
	s_waitcnt lgkmcnt(4)
	v_mfma_f32_32x32x16_bf16 v[112:127], v[172:175], v[180:183], v[112:127]
	v_mfma_f32_32x32x16_bf16 v[96:111], v[172:175], v[184:187], v[96:111]
	v_mfma_f32_32x32x16_bf16 v[48:63], v[172:175], v[188:191], v[48:63]
	v_mfma_f32_32x32x16_bf16 v[32:47], v[172:175], v[192:195], v[32:47]
	v_mfma_f32_32x32x16_bf16 v[80:95], v[176:179], v[180:183], v[80:95]
	v_mfma_f32_32x32x16_bf16 v[64:79], v[176:179], v[184:187], v[64:79]
	v_mfma_f32_32x32x16_bf16 v[16:31], v[176:179], v[188:191], v[16:31]
	v_mfma_f32_32x32x16_bf16 v[0:15], v[176:179], v[192:195], v[0:15]
	s_setprio 0
	s_waitcnt vmcnt(8) lgkmcnt(0)
	s_barrier
	s_setprio 1
	v_mfma_f32_32x32x16_bf16 v[112:127], v[212:215], v[220:223], v[112:127]
	ds_read_b128 v[172:175], v196
	s_add_u32 m0, s5, 0x8000
	v_lshl_add_u64 v[142:143], v[136:137], 0, s[8:9]
	global_load_lds_dwordx4 v[142:143], off
	v_mfma_f32_32x32x16_bf16 v[96:111], v[212:215], v[224:227], v[96:111]
	ds_read_b128 v[176:179], v196 offset:2048
	s_add_u32 m0, s5, 0xa000
	v_lshl_add_u64 v[154:155], v[130:131], 0, s[8:9]
	global_load_lds_dwordx4 v[154:155], off
	v_mfma_f32_32x32x16_bf16 v[48:63], v[212:215], v[228:231], v[48:63]
	ds_read_b128 v[180:183], v197 offset:16384
	s_add_u32 m0, s5, 0xc000
	v_lshl_add_u64 v[142:143], v[140:141], 0, s[8:9]
	global_load_lds_dwordx4 v[142:143], off
	v_mfma_f32_32x32x16_bf16 v[32:47], v[212:215], v[232:235], v[32:47]
	ds_read_b128 v[184:187], v197 offset:18432
	s_add_u32 m0, s5, 0xe000
	v_lshl_add_u64 v[154:155], v[138:139], 0, s[8:9]
	global_load_lds_dwordx4 v[154:155], off
	ds_read_b128 v[212:215], v152
	s_add_u32 s8, s8, 64
	s_addc_u32 s9, s9, 0
	v_mfma_f32_32x32x16_bf16 v[80:95], v[216:219], v[220:223], v[80:95]
	ds_read_b128 v[188:191], v197 offset:20480
	ds_read_b128 v[220:223], v171 offset:16384
	v_mfma_f32_32x32x16_bf16 v[64:79], v[216:219], v[224:227], v[64:79]
	ds_read_b128 v[192:195], v197 offset:22528
	ds_read_b128 v[224:227], v171 offset:18432
	v_mfma_f32_32x32x16_bf16 v[16:31], v[216:219], v[228:231], v[16:31]
	ds_read_b128 v[228:231], v171 offset:20480
	v_mfma_f32_32x32x16_bf16 v[0:15], v[216:219], v[232:235], v[0:15]
	ds_read_b128 v[232:235], v171 offset:22528
	ds_read_b128 v[216:219], v152 offset:2048
	s_xor_b32 s5, s5, 0x10000
	s_add_u32 s0, s0, 0x80
	s_cmpk_lg_i32 s0, 0x1000
	s_setprio 0
	s_cbranch_scc1 .Lgm_p1m_loop
	s_waitcnt lgkmcnt(0)
	s_mov_b64 s[8:9], 0xc0
	s_mov_b64 s[10:11], 0x100
	s_waitcnt vmcnt(0)
	s_waitcnt vmcnt(0)
	s_barrier
	s_and_saveexec_b64 s[0:1], vcc
	s_cbranch_execz .LBB0_929
	s_mov_b32 s4, 0x800000
	v_mul_f32_e32 v130, 0x4b800000, v135
	v_cmp_gt_f32_e32 vcc, s4, v135
	v_lshl_add_u32 v131, v128, 2, 0
	v_add_u32_e32 v131, 0x12000, v131
	v_cndmask_b32_e32 v130, v135, v130, vcc
	v_rsq_f32_e32 v130, v130
	s_nop 0
	v_mul_f32_e32 v135, 0x45800000, v130
	v_cndmask_b32_e32 v130, v130, v135, vcc
	ds_write_b32 v131, v130
